# all three GEMM K-loops: loop-edge SALU rotation + DMA issues interleaved between the ds_reads (no m0 nop pads) + saddr DMA
# baseline (speedup 1.0000x reference)
; #define PG8_STAGE(bufoff, gbase, voff) do { _Pragma("unroll") for (int _i = 0; _i < 2; ++_i) \
;         __builtin_amdgcn_global_load_lds((const unsigned*)((const char*)(gbase) + (voff)[_i]), (PG8_LAS unsigned*)(lds + (bufoff) + ldsw + _i * 8192), 16, 0, 0); } while (0)
; #define PG8_LDA(dst, b, h) do { _Pragma("unroll") for (int m = 0; m < 4; ++m) _Pragma("unroll") for (int k = 0; k < 2; ++k) dst[m][k] = *(const PG8_LAS bf16x8*)(lds + PG8_SA(b, h) + aoff + m * 2048 + k * 1024); } while (0)
; #define PG8_LDB(dst, b, h) do { _Pragma("unroll") for (int n = 0; n < 2; ++n) _Pragma("unroll") for (int k = 0; k < 2; ++k) dst[n][k] = *(const PG8_LAS bf16x8*)(lds + PG8_SB(b, h) + boff + n * 2048 + k * 1024); } while (0)
; #define PG8_MMA(ai, bj, At, Bt) do { __builtin_amdgcn_s_setprio(1); _Pragma("unroll") for (int m = 0; m < 4; ++m) _Pragma("unroll") for (int n = 0; n < 2; ++n) _Pragma("unroll") for (int k = 0; k < 2; ++k) \
;         acc[ai][bj][m][n] = __builtin_amdgcn_mfma_f32_16x16x32_bf16(Bt[n][k], At[m][k], acc[ai][bj][m][n], 0, 0, 0); __builtin_amdgcn_s_setprio(0); } while (0)
; #define PG8_WAIT_V(n) asm volatile("s_waitcnt vmcnt(" #n ")" ::: "memory")
; #define PG8_WAIT_L(n) asm volatile("s_waitcnt lgkmcnt(" #n ")" ::: "memory")
; #define PG8_BAR __builtin_amdgcn_s_barrier()
; #define PG8_SCHED __builtin_amdgcn_sched_barrier(0)
; template <class Epi, class Sched, bool ALIGN_EPI = false, bool SP2 = false>
; __device__ __forceinline__ void gemm_phase(PG8_LAS unsigned char* lds, const Gemm g, const Sched& S, const Epi& E) {
;     ...
;             PG8_LDB(B0, 0, 0); PG8_LDB(B1, 0, 1); PG8_SCHED; PG8_LDA(At, 0, 0); PG8_STAGE(PG8_SA(1, 1), a1 + hstep, voffA);
;             PG8_WAIT_V(8); PG8_WAIT_L(0); PG8_BAR; PG8_MMA(0, 0, At, B0); PG8_MMA(0, 1, At, B1); PG8_BAR; PG8_SCHED;
;             PG8_LDA(At, 0, 1); PG8_STAGE(PG8_SB(0, 0), b2, voffB); PG8_STAGE(PG8_SB(0, 1), b2 + hstep, voffB); PG8_STAGE(PG8_SA(0, 0), a2, voffA);
;             PG8_WAIT_V(8); PG8_WAIT_L(0); PG8_BAR; PG8_MMA(1, 0, At, B0); PG8_MMA(1, 1, At, B1); PG8_BAR; PG8_SCHED;
.LBB0_55:
	s_add_i32 m0, s12, 0xc000
	ds_read_b128 v[64:67], v192
	global_load_lds_dwordx4 v152, s[42:43]
	ds_read_b128 v[68:71], v192 offset:1024
	ds_read_b128 v[72:75], v192 offset:2048
	ds_read_b128 v[76:79], v192 offset:3072
	ds_read_b128 v[156:159], v193
	ds_read_b128 v[168:171], v193 offset:1024
	ds_read_b128 v[172:175], v193 offset:2048
	ds_read_b128 v[176:179], v193 offset:3072
	s_add_i32 m0, s12, 0xe000
	ds_read_b128 v[180:183], v165
	global_load_lds_dwordx4 v154, s[42:43]
	ds_read_b128 v[184:187], v165 offset:1024
	ds_read_b128 v[188:191], v165 offset:2048
	ds_read_b128 v[196:199], v165 offset:3072
	ds_read_b128 v[200:203], v165 offset:4096
	ds_read_b128 v[204:207], v165 offset:5120
	ds_read_b128 v[208:211], v165 offset:6144
	ds_read_b128 v[222:225], v165 offset:7168
	s_waitcnt vmcnt(8)
	s_waitcnt lgkmcnt(0)
	s_barrier
	s_setprio 1
	s_waitcnt lgkmcnt(0)
	v_mfma_f32_16x16x32_bf16 v[140:143], v[64:67], v[180:183], v[140:143]
	v_mfma_f32_16x16x32_bf16 v[136:139], v[72:75], v[180:183], v[136:139]
	v_mfma_f32_16x16x32_bf16 v[124:127], v[64:67], v[188:191], v[124:127]
	v_mfma_f32_16x16x32_bf16 v[120:123], v[72:75], v[188:191], v[120:123]
	v_mfma_f32_16x16x32_bf16 v[108:111], v[64:67], v[200:203], v[108:111]
	v_mfma_f32_16x16x32_bf16 v[104:107], v[72:75], v[200:203], v[104:107]
	v_mfma_f32_16x16x32_bf16 v[92:95], v[64:67], v[208:211], v[92:95]
	v_mfma_f32_16x16x32_bf16 v[88:91], v[72:75], v[208:211], v[88:91]
	v_mfma_f32_16x16x32_bf16 v[140:143], v[68:71], v[184:187], v[140:143]
	v_mfma_f32_16x16x32_bf16 v[136:139], v[76:79], v[184:187], v[136:139]
	v_mfma_f32_16x16x32_bf16 v[124:127], v[68:71], v[196:199], v[124:127]
	v_mfma_f32_16x16x32_bf16 v[120:123], v[76:79], v[196:199], v[120:123]
	v_mfma_f32_16x16x32_bf16 v[108:111], v[68:71], v[204:207], v[108:111]
	v_mfma_f32_16x16x32_bf16 v[104:107], v[76:79], v[204:207], v[104:107]
	v_mfma_f32_16x16x32_bf16 v[92:95], v[68:71], v[222:225], v[92:95]
	v_mfma_f32_16x16x32_bf16 v[88:91], v[76:79], v[222:225], v[88:91]
	s_setprio 0
	s_setprio 1
	v_mfma_f32_16x16x32_bf16 v[132:135], v[156:159], v[180:183], v[132:135]
	v_mfma_f32_16x16x32_bf16 v[128:131], v[172:175], v[180:183], v[128:131]
	v_mfma_f32_16x16x32_bf16 v[116:119], v[156:159], v[188:191], v[116:119]
	v_mfma_f32_16x16x32_bf16 v[112:115], v[172:175], v[188:191], v[112:115]
	v_mfma_f32_16x16x32_bf16 v[100:103], v[156:159], v[200:203], v[100:103]
	v_mfma_f32_16x16x32_bf16 v[96:99], v[172:175], v[200:203], v[96:99]
	v_mfma_f32_16x16x32_bf16 v[84:87], v[156:159], v[208:211], v[84:87]
	v_mfma_f32_16x16x32_bf16 v[80:83], v[172:175], v[208:211], v[80:83]
	v_mfma_f32_16x16x32_bf16 v[132:135], v[168:171], v[184:187], v[132:135]
	v_mfma_f32_16x16x32_bf16 v[128:131], v[176:179], v[184:187], v[128:131]
	v_mfma_f32_16x16x32_bf16 v[116:119], v[168:171], v[196:199], v[116:119]
	v_mfma_f32_16x16x32_bf16 v[112:115], v[176:179], v[196:199], v[112:115]
	v_mfma_f32_16x16x32_bf16 v[100:103], v[168:171], v[204:207], v[100:103]
	v_mfma_f32_16x16x32_bf16 v[96:99], v[176:179], v[204:207], v[96:99]
	v_mfma_f32_16x16x32_bf16 v[84:87], v[168:171], v[222:225], v[84:87]
	v_mfma_f32_16x16x32_bf16 v[80:83], v[176:179], v[222:225], v[80:83]
	s_setprio 0
	s_barrier
	s_add_i32 s28, s72, s8
	s_mov_b32 m0, s28
	ds_read_b128 v[180:183], v165 offset:16384
	global_load_lds_dwordx4 v194, s[50:51]
	s_add_i32 m0, s28, 0x2000
	s_add_u32 s28, s50, 0x80000
	s_addc_u32 s29, s51, 0
	s_add_i32 s72, s73, s8
	ds_read_b128 v[184:187], v165 offset:17408
	global_load_lds_dwordx4 v144, s[50:51]
	s_mov_b32 m0, s72
	ds_read_b128 v[188:191], v165 offset:18432
	global_load_lds_dwordx4 v194, s[28:29]
	s_add_i32 m0, s72, 0x2000
	ds_read_b128 v[196:199], v165 offset:19456
	global_load_lds_dwordx4 v144, s[28:29]
	s_mov_b32 m0, s12
	ds_read_b128 v[200:203], v165 offset:20480
	global_load_lds_dwordx4 v148, s[52:53]
	s_mov_b32 m0, s20
	ds_read_b128 v[204:207], v165 offset:21504
	global_load_lds_dwordx4 v146, s[52:53]
	ds_read_b128 v[208:211], v165 offset:22528
	ds_read_b128 v[222:225], v165 offset:23552
	s_waitcnt vmcnt(8)
	s_waitcnt lgkmcnt(0)
	s_barrier
	s_setprio 1
	s_waitcnt lgkmcnt(0)
	v_mfma_f32_16x16x32_bf16 v[60:63], v[64:67], v[180:183], v[60:63]
	v_mfma_f32_16x16x32_bf16 v[56:59], v[72:75], v[180:183], v[56:59]
	v_mfma_f32_16x16x32_bf16 v[44:47], v[64:67], v[188:191], v[44:47]
	v_mfma_f32_16x16x32_bf16 v[40:43], v[72:75], v[188:191], v[40:43]
	v_mfma_f32_16x16x32_bf16 v[28:31], v[64:67], v[200:203], v[28:31]
	v_mfma_f32_16x16x32_bf16 v[24:27], v[72:75], v[200:203], v[24:27]
	v_mfma_f32_16x16x32_bf16 v[12:15], v[64:67], v[208:211], v[12:15]
	v_mfma_f32_16x16x32_bf16 v[8:11], v[72:75], v[208:211], v[8:11]
	v_mfma_f32_16x16x32_bf16 v[60:63], v[68:71], v[184:187], v[60:63]
	v_mfma_f32_16x16x32_bf16 v[56:59], v[76:79], v[184:187], v[56:59]
	v_mfma_f32_16x16x32_bf16 v[44:47], v[68:71], v[196:199], v[44:47]
	v_mfma_f32_16x16x32_bf16 v[40:43], v[76:79], v[196:199], v[40:43]
	v_mfma_f32_16x16x32_bf16 v[28:31], v[68:71], v[204:207], v[28:31]
	v_mfma_f32_16x16x32_bf16 v[24:27], v[76:79], v[204:207], v[24:27]
	v_mfma_f32_16x16x32_bf16 v[12:15], v[68:71], v[222:225], v[12:15]
	v_mfma_f32_16x16x32_bf16 v[8:11], v[76:79], v[222:225], v[8:11]
	s_setprio 0
	s_setprio 1
	v_mfma_f32_16x16x32_bf16 v[52:55], v[156:159], v[180:183], v[52:55]
	v_mfma_f32_16x16x32_bf16 v[48:51], v[172:175], v[180:183], v[48:51]
	v_mfma_f32_16x16x32_bf16 v[36:39], v[156:159], v[188:191], v[36:39]
	v_mfma_f32_16x16x32_bf16 v[32:35], v[172:175], v[188:191], v[32:35]
	v_mfma_f32_16x16x32_bf16 v[20:23], v[156:159], v[200:203], v[20:23]
	v_mfma_f32_16x16x32_bf16 v[16:19], v[172:175], v[200:203], v[16:19]
	v_mfma_f32_16x16x32_bf16 v[4:7], v[156:159], v[208:211], v[4:7]
	v_mfma_f32_16x16x32_bf16 v[0:3], v[172:175], v[208:211], v[0:3]
	v_mfma_f32_16x16x32_bf16 v[52:55], v[168:171], v[184:187], v[52:55]
	v_mfma_f32_16x16x32_bf16 v[48:51], v[176:179], v[184:187], v[48:51]
	v_mfma_f32_16x16x32_bf16 v[36:39], v[168:171], v[196:199], v[36:39]
	v_mfma_f32_16x16x32_bf16 v[32:35], v[176:179], v[196:199], v[32:35]
	v_mfma_f32_16x16x32_bf16 v[20:23], v[168:171], v[204:207], v[20:23]
	v_mfma_f32_16x16x32_bf16 v[16:19], v[176:179], v[204:207], v[16:19]
	v_mfma_f32_16x16x32_bf16 v[4:7], v[168:171], v[222:225], v[4:7]
	v_mfma_f32_16x16x32_bf16 v[0:3], v[176:179], v[222:225], v[0:3]
	s_setprio 0
	s_barrier
; #define PG8_STAGE(bufoff, gbase, voff) do { _Pragma("unroll") for (int _i = 0; _i < 2; ++_i) \
;         __builtin_amdgcn_global_load_lds((const unsigned*)((const char*)(gbase) + (voff)[_i]), (PG8_LAS unsigned*)(lds + (bufoff) + ldsw + _i * 8192), 16, 0, 0); } while (0)
; #define PG8_LDA(dst, b, h) do { _Pragma("unroll") for (int m = 0; m < 4; ++m) _Pragma("unroll") for (int k = 0; k < 2; ++k) dst[m][k] = *(const PG8_LAS bf16x8*)(lds + PG8_SA(b, h) + aoff + m * 2048 + k * 1024); } while (0)
; #define PG8_LDB(dst, b, h) do { _Pragma("unroll") for (int n = 0; n < 2; ++n) _Pragma("unroll") for (int k = 0; k < 2; ++k) dst[n][k] = *(const PG8_LAS bf16x8*)(lds + PG8_SB(b, h) + boff + n * 2048 + k * 1024); } while (0)
; #define PG8_MMA(ai, bj, At, Bt) do { __builtin_amdgcn_s_setprio(1); _Pragma("unroll") for (int m = 0; m < 4; ++m) _Pragma("unroll") for (int n = 0; n < 2; ++n) _Pragma("unroll") for (int k = 0; k < 2; ++k) \
;         acc[ai][bj][m][n] = __builtin_amdgcn_mfma_f32_16x16x32_bf16(Bt[n][k], At[m][k], acc[ai][bj][m][n], 0, 0, 0); __builtin_amdgcn_s_setprio(0); } while (0)
; #define PG8_WAIT_V(n) asm volatile("s_waitcnt vmcnt(" #n ")" ::: "memory")
; #define PG8_WAIT_L(n) asm volatile("s_waitcnt lgkmcnt(" #n ")" ::: "memory")
; #define PG8_BAR __builtin_amdgcn_s_barrier()
; #define PG8_SCHED __builtin_amdgcn_sched_barrier(0)
; template <class Epi, class Sched, bool ALIGN_EPI = false, bool SP2 = false>
; __device__ __forceinline__ void gemm_phase(PG8_LAS unsigned char* lds, const Gemm g, const Sched& S, const Epi& E) {
;     ...
;         for (int t = 0; t < nt; t += 2) {
;             const bool last = (t == nt - 2);
;             const char* a1 = cA + (size_t)(t + 1) * kstep;
;             const char* a2 = last ? nA : cA + (size_t)(t + 2) * kstep; const char* b2 = last ? nB : cB + (size_t)(t + 2) * kstep;
;     ...
;             PG8_LDB(B0, 1, 0); PG8_LDB(B1, 1, 1); PG8_SCHED; PG8_LDA(At, 1, 0); PG8_STAGE(PG8_SA(0, 1), a2 + hstep, voffA);
;             PG8_WAIT_V(8); PG8_WAIT_L(0); PG8_BAR; PG8_MMA(0, 0, At, B0); PG8_MMA(0, 1, At, B1); PG8_BAR; PG8_SCHED;
;             PG8_LDA(At, 1, 1); PG8_STAGE(PG8_SB(1, 0), b3, voffB); PG8_STAGE(PG8_SB(1, 1), b3 + hstep, voffB); PG8_STAGE(PG8_SA(1, 0), a3, voffA);
;             PG8_WAIT_V(8); PG8_WAIT_L(0); PG8_BAR; PG8_MMA(1, 0, At, B0); PG8_MMA(1, 1, At, B1); PG8_BAR; PG8_SCHED;
	s_add_i32 s72, 0, 0x18000
	s_add_i32 s73, 0, 0x1c000
	s_add_u32 s28, s52, 0x80000
	s_addc_u32 s29, s53, 0
	s_mov_b32 m0, s21
	ds_read_b128 v[64:67], v212
	global_load_lds_dwordx4 v148, s[28:29]
	ds_read_b128 v[68:71], v212 offset:1024
	ds_read_b128 v[72:75], v212 offset:2048
	ds_read_b128 v[76:79], v212 offset:3072
	ds_read_b128 v[156:159], v213
	ds_read_b128 v[168:171], v213 offset:1024
	ds_read_b128 v[172:175], v213 offset:2048
	ds_read_b128 v[176:179], v213 offset:3072
	s_mov_b32 m0, s48
	ds_read_b128 v[180:183], v165 offset:32768
	global_load_lds_dwordx4 v146, s[28:29]
	ds_read_b128 v[184:187], v165 offset:33792
	ds_read_b128 v[188:191], v165 offset:34816
	ds_read_b128 v[196:199], v165 offset:35840
	ds_read_b128 v[200:203], v165 offset:36864
	ds_read_b128 v[204:207], v165 offset:37888
	ds_read_b128 v[208:211], v165 offset:38912
	ds_read_b128 v[222:225], v165 offset:39936
	s_waitcnt vmcnt(8)
	s_waitcnt lgkmcnt(0)
	s_barrier
	s_setprio 1
	s_waitcnt lgkmcnt(0)
	v_mfma_f32_16x16x32_bf16 v[140:143], v[64:67], v[180:183], v[140:143]
	v_mfma_f32_16x16x32_bf16 v[136:139], v[72:75], v[180:183], v[136:139]
	v_mfma_f32_16x16x32_bf16 v[124:127], v[64:67], v[188:191], v[124:127]
	v_mfma_f32_16x16x32_bf16 v[120:123], v[72:75], v[188:191], v[120:123]
	v_mfma_f32_16x16x32_bf16 v[108:111], v[64:67], v[200:203], v[108:111]
	v_mfma_f32_16x16x32_bf16 v[104:107], v[72:75], v[200:203], v[104:107]
	v_mfma_f32_16x16x32_bf16 v[92:95], v[64:67], v[208:211], v[92:95]
	v_mfma_f32_16x16x32_bf16 v[88:91], v[72:75], v[208:211], v[88:91]
	v_mfma_f32_16x16x32_bf16 v[140:143], v[68:71], v[184:187], v[140:143]
	v_mfma_f32_16x16x32_bf16 v[136:139], v[76:79], v[184:187], v[136:139]
	v_mfma_f32_16x16x32_bf16 v[124:127], v[68:71], v[196:199], v[124:127]
	v_mfma_f32_16x16x32_bf16 v[120:123], v[76:79], v[196:199], v[120:123]
	v_mfma_f32_16x16x32_bf16 v[108:111], v[68:71], v[204:207], v[108:111]
	v_mfma_f32_16x16x32_bf16 v[104:107], v[76:79], v[204:207], v[104:107]
	v_mfma_f32_16x16x32_bf16 v[92:95], v[68:71], v[222:225], v[92:95]
	v_mfma_f32_16x16x32_bf16 v[88:91], v[76:79], v[222:225], v[88:91]
	s_setprio 0
	s_setprio 1
	v_mfma_f32_16x16x32_bf16 v[132:135], v[156:159], v[180:183], v[132:135]
	v_mfma_f32_16x16x32_bf16 v[128:131], v[172:175], v[180:183], v[128:131]
	v_mfma_f32_16x16x32_bf16 v[116:119], v[156:159], v[188:191], v[116:119]
	v_mfma_f32_16x16x32_bf16 v[112:115], v[172:175], v[188:191], v[112:115]
	v_mfma_f32_16x16x32_bf16 v[100:103], v[156:159], v[200:203], v[100:103]
	v_mfma_f32_16x16x32_bf16 v[96:99], v[172:175], v[200:203], v[96:99]
	v_mfma_f32_16x16x32_bf16 v[84:87], v[156:159], v[208:211], v[84:87]
	v_mfma_f32_16x16x32_bf16 v[80:83], v[172:175], v[208:211], v[80:83]
	v_mfma_f32_16x16x32_bf16 v[132:135], v[168:171], v[184:187], v[132:135]
	v_mfma_f32_16x16x32_bf16 v[128:131], v[176:179], v[184:187], v[128:131]
	v_mfma_f32_16x16x32_bf16 v[116:119], v[168:171], v[196:199], v[116:119]
	v_mfma_f32_16x16x32_bf16 v[112:115], v[176:179], v[196:199], v[112:115]
	v_mfma_f32_16x16x32_bf16 v[100:103], v[168:171], v[204:207], v[100:103]
	v_mfma_f32_16x16x32_bf16 v[96:99], v[176:179], v[204:207], v[96:99]
	v_mfma_f32_16x16x32_bf16 v[84:87], v[168:171], v[222:225], v[84:87]
	v_mfma_f32_16x16x32_bf16 v[80:83], v[176:179], v[222:225], v[80:83]
	s_setprio 0
	s_barrier
	s_add_i32 s28, s72, s8
	s_add_u32 s98, s50, 0x80
	s_addc_u32 s99, s51, 0
	s_mov_b32 m0, s28
	ds_read_b128 v[180:183], v165 offset:49152
	global_load_lds_dwordx4 v194, s[98:99]
	s_add_i32 m0, s28, 0x2000
	s_add_u32 s28, s50, 0x80080
	s_addc_u32 s29, s51, 0
	s_add_i32 s50, s73, s8
	ds_read_b128 v[184:187], v165 offset:50176
	global_load_lds_dwordx4 v144, s[98:99]
	s_mov_b32 m0, s50
	s_add_u32 s100, s52, 0x80
	s_addc_u32 s101, s53, 0
	ds_read_b128 v[188:191], v165 offset:51200
	global_load_lds_dwordx4 v194, s[28:29]
	s_add_i32 m0, s50, 0x2000
	ds_read_b128 v[196:199], v165 offset:52224
	global_load_lds_dwordx4 v144, s[28:29]
	s_mov_b32 m0, s55
	ds_read_b128 v[200:203], v165 offset:53248
	global_load_lds_dwordx4 v148, s[100:101]
	s_mov_b32 m0, s60
	ds_read_b128 v[204:207], v165 offset:54272
	global_load_lds_dwordx4 v146, s[100:101]
	ds_read_b128 v[208:211], v165 offset:55296
	ds_read_b128 v[222:225], v165 offset:56320
	s_waitcnt vmcnt(8)
	s_waitcnt lgkmcnt(0)
	s_barrier
	s_setprio 1
	s_waitcnt lgkmcnt(0)
	v_mfma_f32_16x16x32_bf16 v[60:63], v[64:67], v[180:183], v[60:63]
	v_mfma_f32_16x16x32_bf16 v[56:59], v[72:75], v[180:183], v[56:59]
	v_mfma_f32_16x16x32_bf16 v[44:47], v[64:67], v[188:191], v[44:47]
	v_mfma_f32_16x16x32_bf16 v[40:43], v[72:75], v[188:191], v[40:43]
	v_mfma_f32_16x16x32_bf16 v[28:31], v[64:67], v[200:203], v[28:31]
	v_mfma_f32_16x16x32_bf16 v[24:27], v[72:75], v[200:203], v[24:27]
	v_mfma_f32_16x16x32_bf16 v[12:15], v[64:67], v[208:211], v[12:15]
	v_mfma_f32_16x16x32_bf16 v[8:11], v[72:75], v[208:211], v[8:11]
	v_mfma_f32_16x16x32_bf16 v[60:63], v[68:71], v[184:187], v[60:63]
	v_mfma_f32_16x16x32_bf16 v[56:59], v[76:79], v[184:187], v[56:59]
	v_mfma_f32_16x16x32_bf16 v[44:47], v[68:71], v[196:199], v[44:47]
	v_mfma_f32_16x16x32_bf16 v[40:43], v[76:79], v[196:199], v[40:43]
	v_mfma_f32_16x16x32_bf16 v[28:31], v[68:71], v[204:207], v[28:31]
	v_mfma_f32_16x16x32_bf16 v[24:27], v[76:79], v[204:207], v[24:27]
	v_mfma_f32_16x16x32_bf16 v[12:15], v[68:71], v[222:225], v[12:15]
	v_mfma_f32_16x16x32_bf16 v[8:11], v[76:79], v[222:225], v[8:11]
	s_setprio 0
	s_setprio 1
	v_mfma_f32_16x16x32_bf16 v[52:55], v[156:159], v[180:183], v[52:55]
	s_add_i32 s71, s71, 2
	v_mfma_f32_16x16x32_bf16 v[48:51], v[172:175], v[180:183], v[48:51]
	s_add_u32 s42, s42, 0x100
	v_mfma_f32_16x16x32_bf16 v[36:39], v[156:159], v[188:191], v[36:39]
	s_addc_u32 s43, s43, 0
	v_mfma_f32_16x16x32_bf16 v[32:35], v[172:175], v[188:191], v[32:35]
	s_add_u32 s67, s67, 0x100
	v_mfma_f32_16x16x32_bf16 v[20:23], v[156:159], v[200:203], v[20:23]
	s_addc_u32 s70, s70, 0
	v_mfma_f32_16x16x32_bf16 v[16:19], v[172:175], v[200:203], v[16:19]
	s_add_u32 s28, s42, 0xfff80080
	v_mfma_f32_16x16x32_bf16 v[4:7], v[156:159], v[208:211], v[4:7]
	s_addc_u32 s29, s43, -1
	v_mfma_f32_16x16x32_bf16 v[0:3], v[172:175], v[208:211], v[0:3]
	s_add_i32 s72, 0, 0x10000
	v_mfma_f32_16x16x32_bf16 v[52:55], v[168:171], v[184:187], v[52:55]
	s_cmp_eq_u32 s71, 28
	v_mfma_f32_16x16x32_bf16 v[48:51], v[176:179], v[184:187], v[48:51]
	s_cselect_b32 s53, s27, s29
	v_mfma_f32_16x16x32_bf16 v[36:39], v[168:171], v[196:199], v[36:39]
	s_cselect_b32 s52, s65, s28
	v_mfma_f32_16x16x32_bf16 v[32:35], v[176:179], v[196:199], v[32:35]
	s_cselect_b32 s51, s25, s70
	v_mfma_f32_16x16x32_bf16 v[20:23], v[168:171], v[204:207], v[20:23]
	s_cselect_b32 s50, s66, s67
	v_mfma_f32_16x16x32_bf16 v[16:19], v[176:179], v[204:207], v[16:19]
	s_add_i32 s73, 0, 0x14000
	v_mfma_f32_16x16x32_bf16 v[4:7], v[168:171], v[222:225], v[4:7]
	v_mfma_f32_16x16x32_bf16 v[0:3], v[176:179], v[222:225], v[0:3]
	s_setprio 0
	s_barrier
	s_cmp_gt_u32 s71, 29
	s_cbranch_scc0 .LBB0_55
	s_and_b64 vcc, exec, s[22:23]
	s_cbranch_vccz .LBB0_58
	s_barrier

; #define PG8_STAGE(bufoff, gbase, voff) do { _Pragma("unroll") for (int _i = 0; _i < 2; ++_i) \
;         __builtin_amdgcn_global_load_lds((const unsigned*)((const char*)(gbase) + (voff)[_i]), (PG8_LAS unsigned*)(lds + (bufoff) + ldsw + _i * 8192), 16, 0, 0); } while (0)
; #define PG8_LDA(dst, b, h) do { _Pragma("unroll") for (int m = 0; m < 4; ++m) _Pragma("unroll") for (int k = 0; k < 2; ++k) dst[m][k] = *(const PG8_LAS bf16x8*)(lds + PG8_SA(b, h) + aoff + m * 2048 + k * 1024); } while (0)
; #define PG8_LDB(dst, b, h) do { _Pragma("unroll") for (int n = 0; n < 2; ++n) _Pragma("unroll") for (int k = 0; k < 2; ++k) dst[n][k] = *(const PG8_LAS bf16x8*)(lds + PG8_SB(b, h) + boff + n * 2048 + k * 1024); } while (0)
; #define PG8_MMA(ai, bj, At, Bt) do { __builtin_amdgcn_s_setprio(1); _Pragma("unroll") for (int m = 0; m < 4; ++m) _Pragma("unroll") for (int n = 0; n < 2; ++n) _Pragma("unroll") for (int k = 0; k < 2; ++k) \
;         acc[ai][bj][m][n] = __builtin_amdgcn_mfma_f32_16x16x32_bf16(Bt[n][k], At[m][k], acc[ai][bj][m][n], 0, 0, 0); __builtin_amdgcn_s_setprio(0); } while (0)
; #define PG8_WAIT_V(n) asm volatile("s_waitcnt vmcnt(" #n ")" ::: "memory")
; #define PG8_WAIT_L(n) asm volatile("s_waitcnt lgkmcnt(" #n ")" ::: "memory")
; #define PG8_BAR __builtin_amdgcn_s_barrier()
; #define PG8_SCHED __builtin_amdgcn_sched_barrier(0)
; template <class Epi, class Sched, bool ALIGN_EPI = false, bool SP2 = false>
; __device__ __forceinline__ void gemm_phase(PG8_LAS unsigned char* lds, const Gemm g, const Sched& S, const Epi& E) {
;     ...
;             PG8_LDB(B0, 0, 0); PG8_LDB(B1, 0, 1); PG8_SCHED; PG8_LDA(At, 0, 0); PG8_STAGE(PG8_SA(1, 1), a1 + hstep, voffA);
;             PG8_WAIT_V(8); PG8_WAIT_L(0); PG8_BAR; PG8_MMA(0, 0, At, B0); PG8_MMA(0, 1, At, B1); PG8_BAR; PG8_SCHED;
;             PG8_LDA(At, 0, 1); PG8_STAGE(PG8_SB(0, 0), b2, voffB); PG8_STAGE(PG8_SB(0, 1), b2 + hstep, voffB); PG8_STAGE(PG8_SA(0, 0), a2, voffA);
;             PG8_WAIT_V(8); PG8_WAIT_L(0); PG8_BAR; PG8_MMA(1, 0, At, B0); PG8_MMA(1, 1, At, B1); PG8_BAR; PG8_SCHED;
.LBB0_402:
	s_add_i32 m0, s77, 0xc000
	ds_read_b128 v[32:35], v192
	global_load_lds_dwordx4 v156, s[26:27]
	ds_read_b128 v[36:39], v192 offset:1024
	ds_read_b128 v[40:43], v192 offset:2048
	ds_read_b128 v[44:47], v192 offset:3072
	ds_read_b128 v[160:163], v193
	ds_read_b128 v[164:167], v193 offset:1024
	ds_read_b128 v[168:171], v193 offset:2048
	ds_read_b128 v[176:179], v193 offset:3072
	s_add_i32 m0, s77, 0xe000
	ds_read_b128 v[180:183], v174
	global_load_lds_dwordx4 v158, s[26:27]
	ds_read_b128 v[184:187], v174 offset:1024
	ds_read_b128 v[188:191], v174 offset:2048
	ds_read_b128 v[196:199], v174 offset:3072
	ds_read_b128 v[200:203], v174 offset:4096
	ds_read_b128 v[204:207], v174 offset:5120
	ds_read_b128 v[208:211], v174 offset:6144
	ds_read_b128 v[234:237], v174 offset:7168
	s_waitcnt vmcnt(8)
	s_waitcnt lgkmcnt(0)
	s_barrier
	s_setprio 1
	s_waitcnt lgkmcnt(0)
	v_mfma_f32_16x16x32_bf16 v[140:143], v[32:35], v[180:183], v[140:143]
	v_mfma_f32_16x16x32_bf16 v[136:139], v[40:43], v[180:183], v[136:139]
	v_mfma_f32_16x16x32_bf16 v[124:127], v[32:35], v[188:191], v[124:127]
	v_mfma_f32_16x16x32_bf16 v[120:123], v[40:43], v[188:191], v[120:123]
	v_mfma_f32_16x16x32_bf16 v[108:111], v[32:35], v[200:203], v[108:111]
	v_mfma_f32_16x16x32_bf16 v[104:107], v[40:43], v[200:203], v[104:107]
	v_mfma_f32_16x16x32_bf16 v[92:95], v[32:35], v[208:211], v[92:95]
	v_mfma_f32_16x16x32_bf16 v[88:91], v[40:43], v[208:211], v[88:91]
	v_mfma_f32_16x16x32_bf16 v[140:143], v[36:39], v[184:187], v[140:143]
	v_mfma_f32_16x16x32_bf16 v[136:139], v[44:47], v[184:187], v[136:139]
	v_mfma_f32_16x16x32_bf16 v[124:127], v[36:39], v[196:199], v[124:127]
	v_mfma_f32_16x16x32_bf16 v[120:123], v[44:47], v[196:199], v[120:123]
	v_mfma_f32_16x16x32_bf16 v[108:111], v[36:39], v[204:207], v[108:111]
	v_mfma_f32_16x16x32_bf16 v[104:107], v[44:47], v[204:207], v[104:107]
	v_mfma_f32_16x16x32_bf16 v[92:95], v[36:39], v[234:237], v[92:95]
	v_mfma_f32_16x16x32_bf16 v[88:91], v[44:47], v[234:237], v[88:91]
	s_setprio 0
	s_setprio 1
	v_mfma_f32_16x16x32_bf16 v[132:135], v[160:163], v[180:183], v[132:135]
	v_mfma_f32_16x16x32_bf16 v[128:131], v[168:171], v[180:183], v[128:131]
	v_mfma_f32_16x16x32_bf16 v[116:119], v[160:163], v[188:191], v[116:119]
	v_mfma_f32_16x16x32_bf16 v[112:115], v[168:171], v[188:191], v[112:115]
	v_mfma_f32_16x16x32_bf16 v[100:103], v[160:163], v[200:203], v[100:103]
	v_mfma_f32_16x16x32_bf16 v[96:99], v[168:171], v[200:203], v[96:99]
	v_mfma_f32_16x16x32_bf16 v[84:87], v[160:163], v[208:211], v[84:87]
	v_mfma_f32_16x16x32_bf16 v[80:83], v[168:171], v[208:211], v[80:83]
	v_mfma_f32_16x16x32_bf16 v[132:135], v[164:167], v[184:187], v[132:135]
	v_mfma_f32_16x16x32_bf16 v[128:131], v[176:179], v[184:187], v[128:131]
	v_mfma_f32_16x16x32_bf16 v[116:119], v[164:167], v[196:199], v[116:119]
	v_mfma_f32_16x16x32_bf16 v[112:115], v[176:179], v[196:199], v[112:115]
	v_mfma_f32_16x16x32_bf16 v[100:103], v[164:167], v[204:207], v[100:103]
	v_mfma_f32_16x16x32_bf16 v[96:99], v[176:179], v[204:207], v[96:99]
	v_mfma_f32_16x16x32_bf16 v[84:87], v[164:167], v[234:237], v[84:87]
	v_mfma_f32_16x16x32_bf16 v[80:83], v[176:179], v[234:237], v[80:83]
	s_setprio 0
	s_barrier
	s_add_i32 s28, s72, s76
	s_mov_b32 m0, s28
	ds_read_b128 v[180:183], v174 offset:16384
	global_load_lds_dwordx4 v148, s[46:47]
	s_add_i32 m0, s28, 0x2000
	s_add_u32 s28, s46, 0x80000
	s_addc_u32 s29, s47, 0
	s_add_i32 s72, s73, s76
	ds_read_b128 v[184:187], v174 offset:17408
	global_load_lds_dwordx4 v144, s[46:47]
	s_mov_b32 m0, s72
	ds_read_b128 v[188:191], v174 offset:18432
	global_load_lds_dwordx4 v148, s[28:29]
	s_add_i32 m0, s72, 0x2000
	ds_read_b128 v[196:199], v174 offset:19456
	global_load_lds_dwordx4 v144, s[28:29]
	s_mov_b32 m0, s77
	ds_read_b128 v[200:203], v174 offset:20480
	global_load_lds_dwordx4 v150, s[48:49]
	s_mov_b32 m0, s79
	ds_read_b128 v[204:207], v174 offset:21504
	global_load_lds_dwordx4 v146, s[48:49]
	ds_read_b128 v[208:211], v174 offset:22528
	ds_read_b128 v[234:237], v174 offset:23552
	s_waitcnt vmcnt(8)
	s_waitcnt lgkmcnt(0)
	s_barrier
	s_setprio 1
	s_waitcnt lgkmcnt(0)
	v_mfma_f32_16x16x32_bf16 v[76:79], v[32:35], v[180:183], v[76:79]
	v_mfma_f32_16x16x32_bf16 v[72:75], v[40:43], v[180:183], v[72:75]
	v_mfma_f32_16x16x32_bf16 v[60:63], v[32:35], v[188:191], v[60:63]
	v_mfma_f32_16x16x32_bf16 v[56:59], v[40:43], v[188:191], v[56:59]
	v_mfma_f32_16x16x32_bf16 v[28:31], v[32:35], v[200:203], v[28:31]
	v_mfma_f32_16x16x32_bf16 v[24:27], v[40:43], v[200:203], v[24:27]
	v_mfma_f32_16x16x32_bf16 v[12:15], v[32:35], v[208:211], v[12:15]
	v_mfma_f32_16x16x32_bf16 v[8:11], v[40:43], v[208:211], v[8:11]
	v_mfma_f32_16x16x32_bf16 v[76:79], v[36:39], v[184:187], v[76:79]
	v_mfma_f32_16x16x32_bf16 v[72:75], v[44:47], v[184:187], v[72:75]
	v_mfma_f32_16x16x32_bf16 v[60:63], v[36:39], v[196:199], v[60:63]
	v_mfma_f32_16x16x32_bf16 v[56:59], v[44:47], v[196:199], v[56:59]
	v_mfma_f32_16x16x32_bf16 v[28:31], v[36:39], v[204:207], v[28:31]
	v_mfma_f32_16x16x32_bf16 v[24:27], v[44:47], v[204:207], v[24:27]
	v_mfma_f32_16x16x32_bf16 v[12:15], v[36:39], v[234:237], v[12:15]
	v_mfma_f32_16x16x32_bf16 v[8:11], v[44:47], v[234:237], v[8:11]
	s_setprio 0
	s_setprio 1
	v_mfma_f32_16x16x32_bf16 v[20:23], v[160:163], v[200:203], v[20:23]
	v_mfma_f32_16x16x32_bf16 v[16:19], v[168:171], v[200:203], v[16:19]
	v_mfma_f32_16x16x32_bf16 v[4:7], v[160:163], v[208:211], v[4:7]
	v_mfma_f32_16x16x32_bf16 v[0:3], v[168:171], v[208:211], v[0:3]
	v_mfma_f32_16x16x32_bf16 v[32:35], v[160:163], v[180:183], v[68:71]
	v_mfma_f32_16x16x32_bf16 v[36:39], v[168:171], v[180:183], v[64:67]
	v_mfma_f32_16x16x32_bf16 v[40:43], v[160:163], v[188:191], v[52:55]
	v_mfma_f32_16x16x32_bf16 v[44:47], v[168:171], v[188:191], v[48:51]
	v_mfma_f32_16x16x32_bf16 v[20:23], v[164:167], v[204:207], v[20:23]
	v_mfma_f32_16x16x32_bf16 v[16:19], v[176:179], v[204:207], v[16:19]
	v_mfma_f32_16x16x32_bf16 v[4:7], v[164:167], v[234:237], v[4:7]
	v_mfma_f32_16x16x32_bf16 v[0:3], v[176:179], v[234:237], v[0:3]
	v_mfma_f32_16x16x32_bf16 v[32:35], v[164:167], v[184:187], v[32:35]
	v_mfma_f32_16x16x32_bf16 v[36:39], v[176:179], v[184:187], v[36:39]
	v_mfma_f32_16x16x32_bf16 v[40:43], v[164:167], v[196:199], v[40:43]
	v_mfma_f32_16x16x32_bf16 v[44:47], v[176:179], v[196:199], v[44:47]
	s_setprio 0
	s_barrier
; #define PG8_STAGE(bufoff, gbase, voff) do { _Pragma("unroll") for (int _i = 0; _i < 2; ++_i) \
;         __builtin_amdgcn_global_load_lds((const unsigned*)((const char*)(gbase) + (voff)[_i]), (PG8_LAS unsigned*)(lds + (bufoff) + ldsw + _i * 8192), 16, 0, 0); } while (0)
; #define PG8_LDA(dst, b, h) do { _Pragma("unroll") for (int m = 0; m < 4; ++m) _Pragma("unroll") for (int k = 0; k < 2; ++k) dst[m][k] = *(const PG8_LAS bf16x8*)(lds + PG8_SA(b, h) + aoff + m * 2048 + k * 1024); } while (0)
; #define PG8_LDB(dst, b, h) do { _Pragma("unroll") for (int n = 0; n < 2; ++n) _Pragma("unroll") for (int k = 0; k < 2; ++k) dst[n][k] = *(const PG8_LAS bf16x8*)(lds + PG8_SB(b, h) + boff + n * 2048 + k * 1024); } while (0)
; #define PG8_MMA(ai, bj, At, Bt) do { __builtin_amdgcn_s_setprio(1); _Pragma("unroll") for (int m = 0; m < 4; ++m) _Pragma("unroll") for (int n = 0; n < 2; ++n) _Pragma("unroll") for (int k = 0; k < 2; ++k) \
;         acc[ai][bj][m][n] = __builtin_amdgcn_mfma_f32_16x16x32_bf16(Bt[n][k], At[m][k], acc[ai][bj][m][n], 0, 0, 0); __builtin_amdgcn_s_setprio(0); } while (0)
; #define PG8_WAIT_V(n) asm volatile("s_waitcnt vmcnt(" #n ")" ::: "memory")
; #define PG8_WAIT_L(n) asm volatile("s_waitcnt lgkmcnt(" #n ")" ::: "memory")
; #define PG8_BAR __builtin_amdgcn_s_barrier()
; #define PG8_SCHED __builtin_amdgcn_sched_barrier(0)
; template <class Epi, class Sched, bool ALIGN_EPI = false, bool SP2 = false>
; __device__ __forceinline__ void gemm_phase(PG8_LAS unsigned char* lds, const Gemm g, const Sched& S, const Epi& E) {
;     ...
;         for (int t = 0; t < nt; t += 2) {
;             const bool last = (t == nt - 2);
;             const char* a1 = cA + (size_t)(t + 1) * kstep;
;             const char* a2 = last ? nA : cA + (size_t)(t + 2) * kstep; const char* b2 = last ? nB : cB + (size_t)(t + 2) * kstep;
;     ...
;             PG8_LDB(B0, 1, 0); PG8_LDB(B1, 1, 1); PG8_SCHED; PG8_LDA(At, 1, 0); PG8_STAGE(PG8_SA(0, 1), a2 + hstep, voffA);
;             PG8_WAIT_V(8); PG8_WAIT_L(0); PG8_BAR; PG8_MMA(0, 0, At, B0); PG8_MMA(0, 1, At, B1); PG8_BAR; PG8_SCHED;
;             PG8_LDA(At, 1, 1); PG8_STAGE(PG8_SB(1, 0), b3, voffB); PG8_STAGE(PG8_SB(1, 1), b3 + hstep, voffB); PG8_STAGE(PG8_SA(1, 0), a3, voffA);
;             PG8_WAIT_V(8); PG8_WAIT_L(0); PG8_BAR; PG8_MMA(1, 0, At, B0); PG8_MMA(1, 1, At, B1); PG8_BAR; PG8_SCHED;
	s_add_i32 s72, 0, 0x18000
	s_add_i32 s73, 0, 0x1c000
	s_add_u32 s28, s48, 0x80000
	s_addc_u32 s29, s49, 0
	s_mov_b32 m0, s80
	ds_read_b128 v[48:51], v212
	global_load_lds_dwordx4 v150, s[28:29]
	ds_read_b128 v[52:55], v212 offset:1024
	ds_read_b128 v[64:67], v212 offset:2048
	ds_read_b128 v[68:71], v212 offset:3072
	ds_read_b128 v[160:163], v213
	ds_read_b128 v[164:167], v213 offset:1024
	ds_read_b128 v[168:171], v213 offset:2048
	ds_read_b128 v[176:179], v213 offset:3072
	s_mov_b32 m0, s12
	ds_read_b128 v[180:183], v174 offset:32768
	global_load_lds_dwordx4 v146, s[28:29]
	ds_read_b128 v[184:187], v174 offset:33792
	ds_read_b128 v[188:191], v174 offset:34816
	ds_read_b128 v[196:199], v174 offset:35840
	ds_read_b128 v[200:203], v174 offset:36864
	ds_read_b128 v[204:207], v174 offset:37888
	ds_read_b128 v[208:211], v174 offset:38912
	ds_read_b128 v[234:237], v174 offset:39936
	s_waitcnt vmcnt(8)
	s_waitcnt lgkmcnt(0)
	s_barrier
	s_setprio 1
	s_waitcnt lgkmcnt(0)
	v_mfma_f32_16x16x32_bf16 v[140:143], v[48:51], v[180:183], v[140:143]
	v_mfma_f32_16x16x32_bf16 v[136:139], v[64:67], v[180:183], v[136:139]
	v_mfma_f32_16x16x32_bf16 v[124:127], v[48:51], v[188:191], v[124:127]
	v_mfma_f32_16x16x32_bf16 v[120:123], v[64:67], v[188:191], v[120:123]
	v_mfma_f32_16x16x32_bf16 v[108:111], v[48:51], v[200:203], v[108:111]
	v_mfma_f32_16x16x32_bf16 v[104:107], v[64:67], v[200:203], v[104:107]
	v_mfma_f32_16x16x32_bf16 v[92:95], v[48:51], v[208:211], v[92:95]
	v_mfma_f32_16x16x32_bf16 v[88:91], v[64:67], v[208:211], v[88:91]
	v_mfma_f32_16x16x32_bf16 v[140:143], v[52:55], v[184:187], v[140:143]
	v_mfma_f32_16x16x32_bf16 v[136:139], v[68:71], v[184:187], v[136:139]
	v_mfma_f32_16x16x32_bf16 v[124:127], v[52:55], v[196:199], v[124:127]
	v_mfma_f32_16x16x32_bf16 v[120:123], v[68:71], v[196:199], v[120:123]
	v_mfma_f32_16x16x32_bf16 v[108:111], v[52:55], v[204:207], v[108:111]
	v_mfma_f32_16x16x32_bf16 v[104:107], v[68:71], v[204:207], v[104:107]
	v_mfma_f32_16x16x32_bf16 v[92:95], v[52:55], v[234:237], v[92:95]
	v_mfma_f32_16x16x32_bf16 v[88:91], v[68:71], v[234:237], v[88:91]
	s_setprio 0
	s_setprio 1
	v_mfma_f32_16x16x32_bf16 v[132:135], v[160:163], v[180:183], v[132:135]
	v_mfma_f32_16x16x32_bf16 v[128:131], v[168:171], v[180:183], v[128:131]
	v_mfma_f32_16x16x32_bf16 v[116:119], v[160:163], v[188:191], v[116:119]
	v_mfma_f32_16x16x32_bf16 v[112:115], v[168:171], v[188:191], v[112:115]
	v_mfma_f32_16x16x32_bf16 v[100:103], v[160:163], v[200:203], v[100:103]
	v_mfma_f32_16x16x32_bf16 v[96:99], v[168:171], v[200:203], v[96:99]
	v_mfma_f32_16x16x32_bf16 v[84:87], v[160:163], v[208:211], v[84:87]
	v_mfma_f32_16x16x32_bf16 v[80:83], v[168:171], v[208:211], v[80:83]
	v_mfma_f32_16x16x32_bf16 v[132:135], v[164:167], v[184:187], v[132:135]
	v_mfma_f32_16x16x32_bf16 v[128:131], v[176:179], v[184:187], v[128:131]
	v_mfma_f32_16x16x32_bf16 v[116:119], v[164:167], v[196:199], v[116:119]
	v_mfma_f32_16x16x32_bf16 v[112:115], v[176:179], v[196:199], v[112:115]
	v_mfma_f32_16x16x32_bf16 v[100:103], v[164:167], v[204:207], v[100:103]
	v_mfma_f32_16x16x32_bf16 v[96:99], v[176:179], v[204:207], v[96:99]
	v_mfma_f32_16x16x32_bf16 v[84:87], v[164:167], v[234:237], v[84:87]
	v_mfma_f32_16x16x32_bf16 v[80:83], v[176:179], v[234:237], v[80:83]
	s_setprio 0
	s_barrier
	s_add_i32 s28, s72, s76
	s_add_u32 s98, s46, 0x80
	s_addc_u32 s99, s47, 0
	s_mov_b32 m0, s28
	ds_read_b128 v[180:183], v174 offset:49152
	global_load_lds_dwordx4 v148, s[98:99]
	s_add_i32 m0, s28, 0x2000
	s_add_u32 s28, s46, 0x80080
	s_addc_u32 s29, s47, 0
	s_add_i32 s46, s73, s76
	ds_read_b128 v[184:187], v174 offset:50176
	global_load_lds_dwordx4 v144, s[98:99]
	s_mov_b32 m0, s46
	s_add_u32 s100, s48, 0x80
	s_addc_u32 s101, s49, 0
	ds_read_b128 v[188:191], v174 offset:51200
	global_load_lds_dwordx4 v148, s[28:29]
	s_add_i32 m0, s46, 0x2000
	ds_read_b128 v[196:199], v174 offset:52224
	global_load_lds_dwordx4 v144, s[28:29]
	s_mov_b32 m0, s78
	ds_read_b128 v[200:203], v174 offset:53248
	global_load_lds_dwordx4 v150, s[100:101]
	s_mov_b32 m0, s86
	ds_read_b128 v[204:207], v174 offset:54272
	global_load_lds_dwordx4 v146, s[100:101]
	ds_read_b128 v[208:211], v174 offset:55296
	ds_read_b128 v[234:237], v174 offset:56320
	s_waitcnt vmcnt(8)
	s_waitcnt lgkmcnt(0)
	s_barrier
	s_setprio 1
	s_waitcnt lgkmcnt(0)
	v_mfma_f32_16x16x32_bf16 v[76:79], v[48:51], v[180:183], v[76:79]
	v_mfma_f32_16x16x32_bf16 v[72:75], v[64:67], v[180:183], v[72:75]
	v_mfma_f32_16x16x32_bf16 v[60:63], v[48:51], v[188:191], v[60:63]
	v_mfma_f32_16x16x32_bf16 v[56:59], v[64:67], v[188:191], v[56:59]
	v_mfma_f32_16x16x32_bf16 v[28:31], v[48:51], v[200:203], v[28:31]
	v_mfma_f32_16x16x32_bf16 v[24:27], v[64:67], v[200:203], v[24:27]
	v_mfma_f32_16x16x32_bf16 v[12:15], v[48:51], v[208:211], v[12:15]
	v_mfma_f32_16x16x32_bf16 v[8:11], v[64:67], v[208:211], v[8:11]
	v_mfma_f32_16x16x32_bf16 v[76:79], v[52:55], v[184:187], v[76:79]
	v_mfma_f32_16x16x32_bf16 v[72:75], v[68:71], v[184:187], v[72:75]
	v_mfma_f32_16x16x32_bf16 v[60:63], v[52:55], v[196:199], v[60:63]
	v_mfma_f32_16x16x32_bf16 v[56:59], v[68:71], v[196:199], v[56:59]
	v_mfma_f32_16x16x32_bf16 v[28:31], v[52:55], v[204:207], v[28:31]
	v_mfma_f32_16x16x32_bf16 v[24:27], v[68:71], v[204:207], v[24:27]
	v_mfma_f32_16x16x32_bf16 v[12:15], v[52:55], v[234:237], v[12:15]
	v_mfma_f32_16x16x32_bf16 v[8:11], v[68:71], v[234:237], v[8:11]
	s_setprio 0
	s_setprio 1
	v_mfma_f32_16x16x32_bf16 v[32:35], v[160:163], v[180:183], v[32:35]
	s_add_i32 s88, s88, 2
	v_mfma_f32_16x16x32_bf16 v[68:71], v[164:167], v[184:187], v[32:35]
	s_add_u32 s26, s26, 0x100
	v_mfma_f32_16x16x32_bf16 v[32:35], v[168:171], v[180:183], v[36:39]
	s_addc_u32 s27, s27, 0
	v_mfma_f32_16x16x32_bf16 v[64:67], v[176:179], v[184:187], v[32:35]
	s_add_u32 s55, s55, 0x100
	v_mfma_f32_16x16x32_bf16 v[32:35], v[160:163], v[188:191], v[40:43]
	s_addc_u32 s61, s61, 0
	v_mfma_f32_16x16x32_bf16 v[52:55], v[164:167], v[196:199], v[32:35]
	s_add_u32 s28, s26, 0xfff80080
	v_mfma_f32_16x16x32_bf16 v[32:35], v[168:171], v[188:191], v[44:47]
	s_addc_u32 s29, s27, -1
	v_mfma_f32_16x16x32_bf16 v[20:23], v[160:163], v[200:203], v[20:23]
	s_add_i32 s72, 0, 0x10000
	v_mfma_f32_16x16x32_bf16 v[16:19], v[168:171], v[200:203], v[16:19]
	s_cmp_eq_u32 s88, 28
	v_mfma_f32_16x16x32_bf16 v[4:7], v[160:163], v[208:211], v[4:7]
	s_cselect_b32 s49, s50, s29
	v_mfma_f32_16x16x32_bf16 v[0:3], v[168:171], v[208:211], v[0:3]
	s_cselect_b32 s48, s51, s28
	v_mfma_f32_16x16x32_bf16 v[48:51], v[176:179], v[196:199], v[32:35]
	s_cselect_b32 s47, s52, s61
	v_mfma_f32_16x16x32_bf16 v[20:23], v[164:167], v[204:207], v[20:23]
	s_cselect_b32 s46, s53, s55
	v_mfma_f32_16x16x32_bf16 v[16:19], v[176:179], v[204:207], v[16:19]
	s_add_i32 s73, 0, 0x14000
	v_mfma_f32_16x16x32_bf16 v[4:7], v[164:167], v[234:237], v[4:7]
	v_mfma_f32_16x16x32_bf16 v[0:3], v[176:179], v[234:237], v[0:3]
	s_setprio 0
	s_barrier
	s_cmp_gt_u32 s88, 29
	s_cbranch_scc0 .LBB0_402
	s_and_b64 vcc, exec, s[22:23]
	s_cbranch_vccz .LBB0_405
	s_barrier
